# byte-phase pin for the gate-GEMM K-loop too (two never-executed pads; later code keeps its phase mod 8)
# speedup vs baseline: 1.0042x; 1.0006x over previous
; __device__ __forceinline__ int otid() { int t = threadIdx.x; asm volatile("" : "+v"(t)); return t; }
; #define PG8_STAGE(bufoff, gbase, voff) do { _Pragma("unroll") for (int _i = 0; _i < 2; ++_i) \
;         __builtin_amdgcn_global_load_lds((const unsigned*)((const char*)(gbase) + (voff)[_i]), (PG8_LAS unsigned*)(lds + (bufoff) + ldsw + _i * 8192), 16, 0, 0); } while (0)
; template <class Epi, class Sched, bool ALIGN_EPI = false, bool SP2 = false>
; __device__ __forceinline__ void gemm_phase(PG8_LAS unsigned char* lds, const Gemm g, const Sched& S, const Epi& E) {
;     const int tid = otid(), wid = __builtin_amdgcn_readfirstlane(tid >> 6), lane = tid & 63, wr = wid >> 2, wc = wid & 3, fr = lane & 15, fq = lane >> 4;
;     const int K = g.K, nt = K / BK;
;     unsigned voffA[2], voffB[2];
; #pragma unroll
;     for (int i = 0; i < 2; ++i) { int R, C; stage_rc(tid * 16 + i * 8192, R, C); const int Rb = Epi::PERM ? ((R & ~31) + perm32(R & 31)) : R;
;         voffA[i] = (unsigned)(R * K + C) * 2u; voffB[i] = (unsigned)(Rb * K + C) * 2u; }
;     const size_t kstep = (size_t)(BK * 2);
;     const size_t hstep = (size_t)HALF * K * 2;
;     const size_t tstep = 2 * hstep;
;     const unsigned ldsw = (unsigned)wid * 1024u;
;     const int aoff = lds_byte(wr * 64 + fr, fq * 8), boff = lds_byte(wc * 32 + fr, fq * 8);
;     ...
;     const char* cA = (const char*)g.A + (size_t)cur.pm * tstep; const char* cB = (const char*)g.Bt + (size_t)cur.pn * tstep;
;     S.a_ready(cur);
;     if constexpr (SP2) {
;         PG8_STAGE(PG8_SB(0, 0), cB, voffB); PG8_STAGE(PG8_SB(0, 1), cB + hstep, voffB); PG8_STAGE(PG8_SA(0, 0), cA, voffA); PG8_STAGE(PG8_SA(0, 1), cA + hstep, voffA);
;         if (wr == 1) PG8_BAR;
;         PG8_WAIT_V(2); PG8_BAR;
;         PG8_STAGE(PG8_SB(1, 0), cB + kstep, voffB); PG8_STAGE(PG8_SA(1, 0), cA + kstep, voffA); PG8_STAGE(PG8_SB(1, 1), cB + hstep + kstep, voffB);
;         PG8_WAIT_V(6); PG8_BAR;
;     } else {
;         PG8_STAGE(PG8_SB(0, 0), cB, voffB); PG8_STAGE(PG8_SA(0, 0), cA, voffA); PG8_STAGE(PG8_SB(0, 1), cB + hstep, voffB); PG8_STAGE(PG8_SA(0, 1), cA + hstep, voffA);
;         if (wr == 1) PG8_BAR;
;         PG8_WAIT_V(4); PG8_BAR;
;         PG8_STAGE(PG8_SB(1, 0), cB + kstep, voffB); PG8_STAGE(PG8_SA(1, 0), cA + kstep, voffA); PG8_STAGE(PG8_SB(1, 1), cB + hstep + kstep, voffB);
;         PG8_WAIT_V(6); PG8_BAR;
;     }
.LBB0_123:
	v_lshrrev_b32_e32 v18, 1, v8
	v_and_b32_e32 v18, 24, v18
	v_and_b32_e32 v9, 15, v8
	v_lshlrev_b32_e32 v19, 1, v18
	v_lshlrev_b32_e32 v8, 2, v8
	s_sext_i32_i8 s13, s14
	v_lshl_or_b32 v150, s27, 6, v9
	v_lshl_or_b32 v9, v9, 6, v19
	s_lshl_b32 s14, s27, 13
	v_and_b32_e32 v8, 32, v8
	v_bitop3_b32 v151, v9, s14, v8 bitop3:0xde
	s_lshl_b32 s14, s26, 5
	s_and_b32 s30, s14, 0x60
	s_lshl_b32 s14, s30, 7
	v_lshl_add_u64 v[10:11], s[6:7], 0, v[0:1]
	v_mov_b32_e32 v139, v1
	v_bitop3_b32 v152, v9, s14, v8 bitop3:0xde
	s_add_i32 s14, s5, 0x18000
	v_lshl_add_u64 v[12:13], s[6:7], 0, v[138:139]
	v_mov_b32_e32 v143, v1
	v_lshl_add_u64 v[8:9], v[10:11], 0, s[34:35]
	s_mov_b32 m0, s14
	s_add_i32 s58, s5, 0x1a000
	v_lshl_add_u64 v[14:15], s[48:49], 0, v[142:143]
	v_mov_b32_e32 v141, v1
	s_waitcnt vmcnt(2)
	s_barrier
	global_load_lds_dwordx4 v[8:9], off
	v_lshl_add_u64 v[8:9], v[12:13], 0, s[34:35]
	s_mov_b32 m0, s58
	s_add_i32 s59, s5, 0x8000
	s_add_i32 s60, s5, 0xa000
	v_lshl_add_u64 v[16:17], s[48:49], 0, v[140:141]
	global_load_lds_dwordx4 v[8:9], off
	v_lshl_add_u64 v[8:9], v[14:15], 0, s[34:35]
	s_mov_b32 m0, s59
	s_add_u32 s26, s6, 0x40080
	global_load_lds_dwordx4 v[8:9], off
	v_lshl_add_u64 v[8:9], v[16:17], 0, s[34:35]
	s_mov_b32 m0, s60
	s_addc_u32 s27, s7, 0
	s_add_i32 s61, s5, 0x1c000
	global_load_lds_dwordx4 v[8:9], off
	v_lshl_add_u64 v[8:9], s[26:27], 0, v[0:1]
	s_mov_b32 m0, s61
	s_add_i32 s62, s5, 0x1e000
	global_load_lds_dwordx4 v[8:9], off
	v_lshl_add_u64 v[8:9], s[26:27], 0, v[138:139]
	s_mov_b32 m0, s62
	s_cmpk_lt_u32 s18, 0x100
	global_load_lds_dwordx4 v[8:9], off
	v_lshlrev_b32_e32 v8, 14, v6
	v_and_b32_e32 v8, 0xffff8000, v8
	v_lshl_add_u32 v5, v5, 11, v8
	v_and_b32_e32 v6, 1, v6
	v_lshl_or_b32 v5, v6, 6, v5
	v_lshl_add_u32 v144, v7, 1, v5
	v_lshlrev_b32_e32 v5, 14, v2
	v_and_b32_e32 v5, 0xffff8000, v5
	s_waitcnt vmcnt(6)
	v_lshl_add_u32 v3, v3, 11, v5
	v_and_b32_e32 v2, 1, v2
	v_lshl_or_b32 v2, v2, 6, v3
	s_cselect_b64 s[26:27], -1, 0
	v_or_b32_e32 v153, s30, v18
	v_mov_b32_e32 v145, v1
	v_lshl_add_u32 v146, v4, 1, v2
	v_mov_b32_e32 v147, v1
	s_mov_b32 s63, 0
	s_barrier
	s_branch .LBB0_126
	s_nop 0

; __device__ __forceinline__ unsigned cvt_pk(float lo, float hi) { f32x2_t v = {lo, hi}; bf16x2_t b = __builtin_convertvector(v, bf16x2_t); return __builtin_bit_cast(unsigned, b); }
; __device__ __forceinline__ float sigmoidf_(float x) { return __builtin_amdgcn_rcpf(1.0f + ex2(-x * LOG2E)); }
;     __device__ __forceinline__ void operator()(const f32x4 (&acc)[2][2][4][2], const Unit& u, int wr, int wc, int fr, int fq) const {
;         const int row0 = u.pm * 256 + wr * 64 + fr, col0 = u.pn * 256 + wc * 32 + 8 * fq;
; #pragma unroll
;         for (int bj = 0; bj < 2; ++bj) {
;             const int c = col0 + bj * 128;
;             const f32x4 b0 = *(const f32x4*)(bias + c), b1 = *(const f32x4*)(bias + c + 4);
; #pragma unroll
;             for (int ai = 0; ai < 2; ++ai)
; #pragma unroll
;                 for (int m = 0; m < 4; ++m) {
;                     const f32x4 v0 = acc[ai][bj][m][0] + b0, v1 = acc[ai][bj][m][1] + b1;
;                     u32x4 w; w.x = cvt_pk(sigmoidf_(v0[0]), sigmoidf_(v0[1])); w.y = cvt_pk(sigmoidf_(v0[2]), sigmoidf_(v0[3]));
;                     w.z = cvt_pk(sigmoidf_(v1[0]), sigmoidf_(v1[1])); w.w = cvt_pk(sigmoidf_(v1[2]), sigmoidf_(v1[3]));
;                     *(u32x4*)(G + (size_t)(row0 + ai * 128 + m * 16) * (3 * DM) + c) = w;
;                 }
;         }
;     }
.LBB0_132:
	v_lshl_or_b32 v160, s13, 8, v153
	v_readlane_b32 s6, v255, 44
	v_ashrrev_i32_e32 v161, 31, v160
	v_readlane_b32 s7, v255, 45
	v_lshl_add_u32 v154, s46, 8, v150
	s_movk_i32 s13, 0x1800
	v_lshl_add_u64 v[148:149], v[160:161], 2, s[6:7]
	global_load_dwordx4 v[106:109], v[148:149], off offset:16
	global_load_dwordx4 v[110:113], v[148:149], off
	v_readlane_b32 s6, v252, 37
	v_readlane_b32 s7, v252, 38
	s_andn2_b64 vcc, exec, s[38:39]
	s_waitcnt vmcnt(0)
	v_pk_add_f32 v[130:131], v[130:131], v[106:107]
	v_pk_add_f32 v[134:135], v[134:135], v[110:111]
	v_pk_add_f32 v[136:137], v[136:137], v[112:113]
	v_mul_f32_e32 v134, 0xbfb8aa3b, v134
	v_mul_f32_e32 v135, 0xbfb8aa3b, v135
	v_exp_f32_e32 v134, v134
	v_exp_f32_e32 v135, v135
	v_pk_add_f32 v[126:127], v[126:127], v[110:111]
	v_pk_add_f32 v[128:129], v[128:129], v[112:113]
	v_add_f32_e32 v134, 1.0, v134
	v_add_f32_e32 v135, 1.0, v135
	v_rcp_f32_e32 v134, v134
	v_rcp_f32_e32 v135, v135
	v_mul_f32_e32 v130, 0xbfb8aa3b, v130
	v_mul_f32_e32 v131, 0xbfb8aa3b, v131
	v_exp_f32_e32 v130, v130
	v_cvt_pk_bf16_f32 v156, v134, v135
	v_mul_f32_e32 v134, 0xbfb8aa3b, v136
	v_mul_f32_e32 v135, 0xbfb8aa3b, v137
	v_pk_add_f32 v[136:137], v[124:125], v[108:109]
	v_pk_add_f32 v[124:125], v[122:123], v[106:107]
	v_mul_f32_e32 v122, 0xbfb8aa3b, v126
	v_mul_f32_e32 v123, 0xbfb8aa3b, v127
	v_exp_f32_e32 v122, v122
	v_exp_f32_e32 v123, v123
	v_mul_f32_e32 v126, 0xbfb8aa3b, v129
	v_mul_f32_e32 v124, 0xbfb8aa3b, v124
	v_add_f32_e32 v122, 1.0, v122
	v_add_f32_e32 v123, 1.0, v123
	v_rcp_f32_e32 v122, v122
	v_rcp_f32_e32 v123, v123
	v_mul_f32_e32 v125, 0xbfb8aa3b, v125
	v_exp_f32_e32 v126, v126
	v_exp_f32_e32 v124, v124
	v_cvt_pk_bf16_f32 v122, v122, v123
	v_mul_f32_e32 v123, 0xbfb8aa3b, v128
	v_exp_f32_e32 v123, v123
	v_exp_f32_e32 v125, v125
	v_add_f32_e32 v126, 1.0, v126
	v_add_f32_e32 v124, 1.0, v124
	v_add_f32_e32 v123, 1.0, v123
	v_add_f32_e32 v125, 1.0, v125
	v_rcp_f32_e32 v123, v123
	v_rcp_f32_e32 v126, v126
	v_rcp_f32_e32 v124, v124
	v_rcp_f32_e32 v125, v125
	v_exp_f32_e32 v131, v131
	v_cvt_pk_bf16_f32 v123, v123, v126
	v_mul_f32_e32 v126, 0xbfb8aa3b, v137
	v_cvt_pk_bf16_f32 v124, v124, v125
	v_mul_f32_e32 v125, 0xbfb8aa3b, v136
	v_exp_f32_e32 v125, v125
	v_exp_f32_e32 v126, v126
	v_exp_f32_e32 v134, v134
	v_exp_f32_e32 v135, v135
	v_add_f32_e32 v130, 1.0, v130
	v_add_f32_e32 v131, 1.0, v131
	v_add_f32_e32 v125, 1.0, v125
	v_add_f32_e32 v126, 1.0, v126
	v_add_f32_e32 v134, 1.0, v134
	v_add_f32_e32 v135, 1.0, v135
	v_rcp_f32_e32 v130, v130
	v_rcp_f32_e32 v131, v131
	v_rcp_f32_e32 v125, v125
	v_rcp_f32_e32 v126, v126
	v_rcp_f32_e32 v134, v134
	v_rcp_f32_e32 v135, v135
	v_pk_add_f32 v[132:133], v[132:133], v[108:109]
	v_cvt_pk_bf16_f32 v158, v130, v131
	v_mul_f32_e32 v130, 0xbfb8aa3b, v132
	v_mul_f32_e32 v131, 0xbfb8aa3b, v133
	v_mov_b64_e32 v[132:133], s[6:7]
	v_cvt_pk_bf16_f32 v125, v125, v126
	v_or_b32_e32 v126, 16, v154
	v_cvt_pk_bf16_f32 v157, v134, v135
	v_lshlrev_b64 v[134:135], 1, v[160:161]
	v_mad_i64_i32 v[126:127], s[6:7], v126, s13, v[132:133]
	v_lshl_add_u64 v[126:127], v[126:127], 0, v[134:135]
	v_pk_add_f32 v[118:119], v[118:119], v[110:111]
	global_store_dwordx4 v[126:127], v[122:125], off
	v_pk_add_f32 v[120:121], v[120:121], v[112:113]
	v_pk_add_f32 v[114:115], v[114:115], v[106:107]
	v_pk_add_f32 v[122:123], v[116:117], v[108:109]
	v_mul_f32_e32 v116, 0xbfb8aa3b, v118
	v_mul_f32_e32 v117, 0xbfb8aa3b, v119
	v_exp_f32_e32 v116, v116
	v_exp_f32_e32 v117, v117
	v_mul_f32_e32 v118, 0xbfb8aa3b, v121
	v_mul_f32_e32 v114, 0xbfb8aa3b, v114
	v_add_f32_e32 v116, 1.0, v116
	v_add_f32_e32 v117, 1.0, v117
	v_rcp_f32_e32 v116, v116
	v_rcp_f32_e32 v117, v117
	v_mul_f32_e32 v115, 0xbfb8aa3b, v115
	v_exp_f32_e32 v118, v118
	v_exp_f32_e32 v114, v114
	v_cvt_pk_bf16_f32 v116, v116, v117
	v_mul_f32_e32 v117, 0xbfb8aa3b, v120
	v_exp_f32_e32 v117, v117
	v_exp_f32_e32 v115, v115
	v_add_f32_e32 v118, 1.0, v118
	v_add_f32_e32 v114, 1.0, v114
	v_add_f32_e32 v117, 1.0, v117
	v_add_f32_e32 v115, 1.0, v115
	v_rcp_f32_e32 v117, v117
	v_rcp_f32_e32 v118, v118
	v_rcp_f32_e32 v114, v114
	v_rcp_f32_e32 v115, v115
	v_pk_add_f32 v[102:103], v[102:103], v[110:111]
	v_cvt_pk_bf16_f32 v117, v117, v118
	v_pk_add_f32 v[104:105], v[104:105], v[112:113]
	v_cvt_pk_bf16_f32 v118, v114, v115
	v_mul_f32_e32 v114, 0xbfb8aa3b, v122
	v_mul_f32_e32 v115, 0xbfb8aa3b, v123
	v_exp_f32_e32 v114, v114
	v_exp_f32_e32 v115, v115
	v_pk_add_f32 v[98:99], v[98:99], v[106:107]
	v_pk_add_f32 v[94:95], v[94:95], v[110:111]
	v_add_f32_e32 v114, 1.0, v114
	v_add_f32_e32 v115, 1.0, v115
	v_rcp_f32_e32 v114, v114
	v_rcp_f32_e32 v115, v115
	v_mul_f32_e32 v98, 0xbfb8aa3b, v98
	v_mul_f32_e32 v99, 0xbfb8aa3b, v99
	v_exp_f32_e32 v98, v98
	v_cvt_pk_bf16_f32 v119, v114, v115
	v_or_b32_e32 v114, 32, v154
	v_mad_i64_i32 v[114:115], s[6:7], v114, s13, v[132:133]
	v_lshl_add_u64 v[114:115], v[114:115], 0, v[134:135]
	global_store_dwordx4 v[114:115], v[116:119], off
	v_exp_f32_e32 v99, v99
	v_add_f32_e32 v98, 1.0, v98
	v_pk_add_f32 v[116:117], v[100:101], v[108:109]
	v_mul_f32_e32 v100, 0xbfb8aa3b, v102
	v_mul_f32_e32 v101, 0xbfb8aa3b, v103
	v_exp_f32_e32 v100, v100
	v_exp_f32_e32 v101, v101
	v_mul_f32_e32 v102, 0xbfb8aa3b, v105
	v_exp_f32_e32 v102, v102
	v_add_f32_e32 v100, 1.0, v100
	v_add_f32_e32 v101, 1.0, v101
	v_rcp_f32_e32 v100, v100
	v_rcp_f32_e32 v101, v101
	v_add_f32_e32 v102, 1.0, v102
	v_add_f32_e32 v99, 1.0, v99
	v_rcp_f32_e32 v102, v102
	v_cvt_pk_bf16_f32 v100, v100, v101
	v_mul_f32_e32 v101, 0xbfb8aa3b, v104
	v_exp_f32_e32 v101, v101
	v_rcp_f32_e32 v98, v98
	v_rcp_f32_e32 v99, v99
	v_pk_add_f32 v[96:97], v[96:97], v[112:113]
	v_add_f32_e32 v101, 1.0, v101
; __device__ __forceinline__ unsigned cvt_pk(float lo, float hi) { f32x2_t v = {lo, hi}; bf16x2_t b = __builtin_convertvector(v, bf16x2_t); return __builtin_bit_cast(unsigned, b); }
; __device__ __forceinline__ float sigmoidf_(float x) { return __builtin_amdgcn_rcpf(1.0f + ex2(-x * LOG2E)); }
;     __device__ __forceinline__ void operator()(const f32x4 (&acc)[2][2][4][2], const Unit& u, int wr, int wc, int fr, int fq) const {
;         const int row0 = u.pm * 256 + wr * 64 + fr, col0 = u.pn * 256 + wc * 32 + 8 * fq;
; #pragma unroll
;         for (int bj = 0; bj < 2; ++bj) {
;             const int c = col0 + bj * 128;
;             const f32x4 b0 = *(const f32x4*)(bias + c), b1 = *(const f32x4*)(bias + c + 4);
; #pragma unroll
;             for (int ai = 0; ai < 2; ++ai)
; #pragma unroll
;                 for (int m = 0; m < 4; ++m) {
;                     const f32x4 v0 = acc[ai][bj][m][0] + b0, v1 = acc[ai][bj][m][1] + b1;
;                     u32x4 w; w.x = cvt_pk(sigmoidf_(v0[0]), sigmoidf_(v0[1])); w.y = cvt_pk(sigmoidf_(v0[2]), sigmoidf_(v0[3]));
;                     w.z = cvt_pk(sigmoidf_(v1[0]), sigmoidf_(v1[1])); w.w = cvt_pk(sigmoidf_(v1[2]), sigmoidf_(v1[3]));
;                     *(u32x4*)(G + (size_t)(row0 + ai * 128 + m * 16) * (3 * DM) + c) = w;
;                 }
;         }
;     }
	v_rcp_f32_e32 v101, v101
	v_pk_add_f32 v[90:91], v[90:91], v[106:107]
	v_pk_add_f32 v[86:87], v[86:87], v[110:111]
	v_mul_f32_e32 v90, 0xbfb8aa3b, v90
	v_cvt_pk_bf16_f32 v101, v101, v102
	v_cvt_pk_bf16_f32 v102, v98, v99
	v_mul_f32_e32 v98, 0xbfb8aa3b, v116
	v_mul_f32_e32 v99, 0xbfb8aa3b, v117
	v_exp_f32_e32 v98, v98
	v_exp_f32_e32 v99, v99
	v_mul_f32_e32 v91, 0xbfb8aa3b, v91
	v_exp_f32_e32 v90, v90
	v_add_f32_e32 v98, 1.0, v98
	v_add_f32_e32 v99, 1.0, v99
	v_rcp_f32_e32 v98, v98
	v_rcp_f32_e32 v99, v99
	v_exp_f32_e32 v91, v91
	v_add_f32_e32 v90, 1.0, v90
	v_rcp_f32_e32 v90, v90
	v_cvt_pk_bf16_f32 v103, v98, v99
	v_or_b32_e32 v98, 48, v154
	v_mad_i64_i32 v[98:99], s[6:7], v98, s13, v[132:133]
	v_lshl_add_u64 v[98:99], v[98:99], 0, v[134:135]
	global_store_dwordx4 v[98:99], v[100:103], off
	v_add_f32_e32 v91, 1.0, v91
	v_rcp_f32_e32 v91, v91
	v_pk_add_f32 v[100:101], v[92:93], v[108:109]
	v_mul_f32_e32 v92, 0xbfb8aa3b, v94
	v_mul_f32_e32 v93, 0xbfb8aa3b, v95
	v_exp_f32_e32 v92, v92
	v_exp_f32_e32 v93, v93
	v_mul_f32_e32 v94, 0xbfb8aa3b, v97
	v_exp_f32_e32 v94, v94
	v_add_f32_e32 v92, 1.0, v92
	v_add_f32_e32 v93, 1.0, v93
	v_rcp_f32_e32 v92, v92
	v_rcp_f32_e32 v93, v93
	v_add_f32_e32 v94, 1.0, v94
	v_rcp_f32_e32 v94, v94
	v_add_u32_e32 v102, 0x80, v154
	v_cvt_pk_bf16_f32 v92, v92, v93
	v_mul_f32_e32 v93, 0xbfb8aa3b, v96
	v_exp_f32_e32 v93, v93
	v_pk_add_f32 v[88:89], v[88:89], v[112:113]
	v_pk_add_f32 v[82:83], v[82:83], v[106:107]
	v_pk_add_f32 v[78:79], v[78:79], v[110:111]
	v_add_f32_e32 v93, 1.0, v93
	v_rcp_f32_e32 v93, v93
	v_mul_f32_e32 v82, 0xbfb8aa3b, v82
	v_mul_f32_e32 v83, 0xbfb8aa3b, v83
	v_exp_f32_e32 v82, v82
	v_cvt_pk_bf16_f32 v93, v93, v94
	v_cvt_pk_bf16_f32 v94, v90, v91
	v_mul_f32_e32 v90, 0xbfb8aa3b, v100
	v_mul_f32_e32 v91, 0xbfb8aa3b, v101
	v_exp_f32_e32 v90, v90
	v_exp_f32_e32 v91, v91
	v_exp_f32_e32 v83, v83
	v_add_f32_e32 v82, 1.0, v82
	v_add_f32_e32 v90, 1.0, v90
	v_add_f32_e32 v91, 1.0, v91
	v_rcp_f32_e32 v90, v90
	v_rcp_f32_e32 v91, v91
	v_add_f32_e32 v83, 1.0, v83
	v_rcp_f32_e32 v82, v82
	v_rcp_f32_e32 v83, v83
	v_cvt_pk_bf16_f32 v95, v90, v91
	v_mad_i64_i32 v[90:91], s[6:7], v102, s13, v[132:133]
	v_lshl_add_u64 v[90:91], v[90:91], 0, v[134:135]
	global_store_dwordx4 v[90:91], v[92:95], off
	v_pk_add_f32 v[80:81], v[80:81], v[112:113]
	v_pk_add_f32 v[74:75], v[74:75], v[106:107]
	v_pk_add_f32 v[92:93], v[84:85], v[108:109]
	v_mul_f32_e32 v84, 0xbfb8aa3b, v86
	v_mul_f32_e32 v85, 0xbfb8aa3b, v87
	v_exp_f32_e32 v84, v84
	v_exp_f32_e32 v85, v85
	v_mul_f32_e32 v86, 0xbfb8aa3b, v89
	v_exp_f32_e32 v86, v86
	v_add_f32_e32 v84, 1.0, v84
	v_add_f32_e32 v85, 1.0, v85
	v_rcp_f32_e32 v84, v84
	v_rcp_f32_e32 v85, v85
	v_add_f32_e32 v86, 1.0, v86
	v_rcp_f32_e32 v86, v86
	v_mul_f32_e32 v74, 0xbfb8aa3b, v74
	v_cvt_pk_bf16_f32 v84, v84, v85
	v_mul_f32_e32 v85, 0xbfb8aa3b, v88
	v_exp_f32_e32 v85, v85
	v_mul_f32_e32 v75, 0xbfb8aa3b, v75
	v_exp_f32_e32 v74, v74
	v_exp_f32_e32 v75, v75
	v_add_f32_e32 v85, 1.0, v85
	v_rcp_f32_e32 v85, v85
	v_add_f32_e32 v74, 1.0, v74
	v_add_f32_e32 v75, 1.0, v75
	v_rcp_f32_e32 v74, v74
	v_cvt_pk_bf16_f32 v85, v85, v86
	v_cvt_pk_bf16_f32 v86, v82, v83
	v_mul_f32_e32 v82, 0xbfb8aa3b, v92
	v_mul_f32_e32 v83, 0xbfb8aa3b, v93
	v_exp_f32_e32 v82, v82
	v_exp_f32_e32 v83, v83
	v_rcp_f32_e32 v75, v75
	v_pk_add_f32 v[70:71], v[70:71], v[110:111]
	v_add_f32_e32 v82, 1.0, v82
	v_add_f32_e32 v83, 1.0, v83
	v_rcp_f32_e32 v82, v82
	v_rcp_f32_e32 v83, v83
	v_pk_add_f32 v[72:73], v[72:73], v[112:113]
	v_exp_f32_e32 v130, v130
	v_exp_f32_e32 v131, v131
	v_cvt_pk_bf16_f32 v87, v82, v83
	v_add_u32_e32 v82, 0x90, v154
	v_mad_i64_i32 v[82:83], s[6:7], v82, s13, v[132:133]
	v_lshl_add_u64 v[82:83], v[82:83], 0, v[134:135]
	global_store_dwordx4 v[82:83], v[84:87], off
	v_add_f32_e32 v130, 1.0, v130
	v_add_f32_e32 v131, 1.0, v131
	v_pk_add_f32 v[84:85], v[76:77], v[108:109]
	v_mul_f32_e32 v76, 0xbfb8aa3b, v78
	v_mul_f32_e32 v77, 0xbfb8aa3b, v79
	v_exp_f32_e32 v76, v76
	v_exp_f32_e32 v77, v77
	v_mul_f32_e32 v78, 0xbfb8aa3b, v81
	v_exp_f32_e32 v78, v78
	v_add_f32_e32 v76, 1.0, v76
	v_add_f32_e32 v77, 1.0, v77
	v_rcp_f32_e32 v76, v76
	v_rcp_f32_e32 v77, v77
	v_add_f32_e32 v78, 1.0, v78
	v_rcp_f32_e32 v78, v78
	v_rcp_f32_e32 v130, v130
	v_cvt_pk_bf16_f32 v76, v76, v77
	v_mul_f32_e32 v77, 0xbfb8aa3b, v80
	v_exp_f32_e32 v77, v77
	v_rcp_f32_e32 v131, v131
	v_add_f32_e32 v77, 1.0, v77
	v_rcp_f32_e32 v77, v77
	v_cvt_pk_bf16_f32 v159, v130, v131
	v_mad_i64_i32 v[130:131], s[6:7], v154, s13, v[132:133]
	v_cvt_pk_bf16_f32 v77, v77, v78
	v_cvt_pk_bf16_f32 v78, v74, v75
	v_mul_f32_e32 v74, 0xbfb8aa3b, v84
	v_mul_f32_e32 v75, 0xbfb8aa3b, v85
	v_exp_f32_e32 v74, v74
	v_exp_f32_e32 v75, v75
	v_lshl_add_u64 v[130:131], v[130:131], 0, v[134:135]
	global_store_dwordx4 v[130:131], v[156:159], off
	v_add_f32_e32 v74, 1.0, v74
	v_add_f32_e32 v75, 1.0, v75
	v_rcp_f32_e32 v74, v74
	v_rcp_f32_e32 v75, v75
	s_nop 0
	v_cvt_pk_bf16_f32 v79, v74, v75
	v_add_u32_e32 v74, 0xa0, v154
	v_mad_i64_i32 v[74:75], s[6:7], v74, s13, v[132:133]
	v_lshl_add_u64 v[74:75], v[74:75], 0, v[134:135]
	global_store_dwordx4 v[74:75], v[76:79], off
	s_nop 1
	v_pk_add_f32 v[76:77], v[68:69], v[108:109]
	v_pk_add_f32 v[68:69], v[66:67], v[106:107]
	v_mul_f32_e32 v66, 0xbfb8aa3b, v70
	v_mul_f32_e32 v67, 0xbfb8aa3b, v71
	v_exp_f32_e32 v66, v66
	v_exp_f32_e32 v67, v67
	v_mul_f32_e32 v70, 0xbfb8aa3b, v73
	v_mul_f32_e32 v68, 0xbfb8aa3b, v68
	v_add_f32_e32 v66, 1.0, v66
	v_add_f32_e32 v67, 1.0, v67
	v_rcp_f32_e32 v66, v66
	v_rcp_f32_e32 v67, v67
	v_mul_f32_e32 v69, 0xbfb8aa3b, v69
	v_exp_f32_e32 v70, v70
	v_exp_f32_e32 v68, v68
	v_cvt_pk_bf16_f32 v66, v66, v67
	v_mul_f32_e32 v67, 0xbfb8aa3b, v72
	v_exp_f32_e32 v67, v67
	v_exp_f32_e32 v69, v69
	v_add_f32_e32 v70, 1.0, v70
	v_add_f32_e32 v68, 1.0, v68
	v_add_f32_e32 v67, 1.0, v67
	v_add_f32_e32 v69, 1.0, v69
	v_rcp_f32_e32 v67, v67
	v_rcp_f32_e32 v70, v70
	v_rcp_f32_e32 v68, v68
	v_rcp_f32_e32 v69, v69
	v_cvt_pk_bf16_f32 v67, v67, v70
	v_mul_f32_e32 v70, 0xbfb8aa3b, v77
	v_cvt_pk_bf16_f32 v68, v68, v69
	v_mul_f32_e32 v69, 0xbfb8aa3b, v76
	v_exp_f32_e32 v69, v69
	v_exp_f32_e32 v70, v70
	v_add_f32_e32 v69, 1.0, v69
	v_add_f32_e32 v70, 1.0, v70
	v_rcp_f32_e32 v69, v69
	v_rcp_f32_e32 v70, v70
	s_nop 0
	v_cvt_pk_bf16_f32 v69, v69, v70
	v_add_u32_e32 v70, 0xb0, v154
	v_mad_i64_i32 v[70:71], s[6:7], v70, s13, v[132:133]
	v_lshl_add_u64 v[76:77], v[70:71], 0, v[134:135]
	global_store_dwordx4 v[76:77], v[66:69], off
	global_load_dwordx4 v[66:69], v[148:149], off offset:528
	s_nop 0
	global_load_dwordx4 v[70:73], v[148:149], off offset:512
	s_mov_b64 s[6:7], -1
	s_waitcnt vmcnt(1)
; __device__ __forceinline__ unsigned cvt_pk(float lo, float hi) { f32x2_t v = {lo, hi}; bf16x2_t b = __builtin_convertvector(v, bf16x2_t); return __builtin_bit_cast(unsigned, b); }
; __device__ __forceinline__ float sigmoidf_(float x) { return __builtin_amdgcn_rcpf(1.0f + ex2(-x * LOG2E)); }
;     __device__ __forceinline__ void operator()(const f32x4 (&acc)[2][2][4][2], const Unit& u, int wr, int wc, int fr, int fq) const {
;         const int row0 = u.pm * 256 + wr * 64 + fr, col0 = u.pn * 256 + wc * 32 + 8 * fq;
; #pragma unroll
;         for (int bj = 0; bj < 2; ++bj) {
;             const int c = col0 + bj * 128;
;             const f32x4 b0 = *(const f32x4*)(bias + c), b1 = *(const f32x4*)(bias + c + 4);
; #pragma unroll
;             for (int ai = 0; ai < 2; ++ai)
; #pragma unroll
;                 for (int m = 0; m < 4; ++m) {
;                     const f32x4 v0 = acc[ai][bj][m][0] + b0, v1 = acc[ai][bj][m][1] + b1;
;                     u32x4 w; w.x = cvt_pk(sigmoidf_(v0[0]), sigmoidf_(v0[1])); w.y = cvt_pk(sigmoidf_(v0[2]), sigmoidf_(v0[3]));
;                     w.z = cvt_pk(sigmoidf_(v1[0]), sigmoidf_(v1[1])); w.w = cvt_pk(sigmoidf_(v1[2]), sigmoidf_(v1[3]));
;                     *(u32x4*)(G + (size_t)(row0 + ai * 128 + m * 16) * (3 * DM) + c) = w;
;                 }
;         }
;     }
	v_pk_add_f32 v[78:79], v[60:61], v[68:69]
	s_waitcnt vmcnt(0)
	v_pk_add_f32 v[62:63], v[62:63], v[70:71]
	v_pk_add_f32 v[60:61], v[58:59], v[66:67]
	v_mul_f32_e32 v58, 0xbfb8aa3b, v62
	v_mul_f32_e32 v59, 0xbfb8aa3b, v63
	v_exp_f32_e32 v58, v58
	v_exp_f32_e32 v59, v59
	v_pk_add_f32 v[64:65], v[64:65], v[72:73]
	v_mul_f32_e32 v60, 0xbfb8aa3b, v60
	v_add_f32_e32 v58, 1.0, v58
	v_add_f32_e32 v59, 1.0, v59
	v_rcp_f32_e32 v58, v58
	v_rcp_f32_e32 v59, v59
	v_mul_f32_e32 v62, 0xbfb8aa3b, v65
	v_mul_f32_e32 v61, 0xbfb8aa3b, v61
	v_exp_f32_e32 v62, v62
	v_cvt_pk_bf16_f32 v58, v58, v59
	v_mul_f32_e32 v59, 0xbfb8aa3b, v64
	v_exp_f32_e32 v59, v59
	v_exp_f32_e32 v60, v60
	v_exp_f32_e32 v61, v61
	v_add_f32_e32 v62, 1.0, v62
	v_add_f32_e32 v59, 1.0, v59
	v_add_f32_e32 v60, 1.0, v60
	v_add_f32_e32 v61, 1.0, v61
	v_rcp_f32_e32 v59, v59
	v_rcp_f32_e32 v62, v62
	v_rcp_f32_e32 v60, v60
	v_rcp_f32_e32 v61, v61
	v_pk_add_f32 v[54:55], v[54:55], v[70:71]
	v_cvt_pk_bf16_f32 v59, v59, v62
	v_mul_f32_e32 v62, 0xbfb8aa3b, v79
	v_cvt_pk_bf16_f32 v60, v60, v61
	v_mul_f32_e32 v61, 0xbfb8aa3b, v78
	v_exp_f32_e32 v61, v61
	v_exp_f32_e32 v62, v62
	v_pk_add_f32 v[56:57], v[56:57], v[72:73]
	v_pk_add_f32 v[46:47], v[46:47], v[70:71]
	v_add_f32_e32 v61, 1.0, v61
	v_add_f32_e32 v62, 1.0, v62
	v_rcp_f32_e32 v61, v61
	v_rcp_f32_e32 v62, v62
	v_pk_add_f32 v[48:49], v[48:49], v[72:73]
	v_pk_add_f32 v[38:39], v[38:39], v[70:71]
	v_pk_add_f32 v[40:41], v[40:41], v[72:73]
	v_cvt_pk_bf16_f32 v61, v61, v62
	global_store_dwordx4 v[130:131], v[58:61], off offset:256
	v_pk_add_f32 v[30:31], v[30:31], v[70:71]
	v_pk_add_f32 v[32:33], v[32:33], v[72:73]
	v_pk_add_f32 v[58:59], v[52:53], v[68:69]
	v_pk_add_f32 v[52:53], v[50:51], v[66:67]
	v_mul_f32_e32 v50, 0xbfb8aa3b, v54
	v_mul_f32_e32 v51, 0xbfb8aa3b, v55
	v_exp_f32_e32 v50, v50
	v_exp_f32_e32 v51, v51
	v_mul_f32_e32 v54, 0xbfb8aa3b, v57
	v_mul_f32_e32 v52, 0xbfb8aa3b, v52
	v_add_f32_e32 v50, 1.0, v50
	v_add_f32_e32 v51, 1.0, v51
	v_rcp_f32_e32 v50, v50
	v_rcp_f32_e32 v51, v51
	v_mul_f32_e32 v53, 0xbfb8aa3b, v53
	v_exp_f32_e32 v54, v54
	v_exp_f32_e32 v52, v52
	v_cvt_pk_bf16_f32 v50, v50, v51
	v_mul_f32_e32 v51, 0xbfb8aa3b, v56
	v_exp_f32_e32 v51, v51
	v_exp_f32_e32 v53, v53
	v_add_f32_e32 v54, 1.0, v54
	v_add_f32_e32 v52, 1.0, v52
	v_add_f32_e32 v51, 1.0, v51
	v_add_f32_e32 v53, 1.0, v53
	v_rcp_f32_e32 v51, v51
	v_rcp_f32_e32 v54, v54
	v_rcp_f32_e32 v52, v52
	v_rcp_f32_e32 v53, v53
	v_pk_add_f32 v[22:23], v[22:23], v[70:71]
	v_cvt_pk_bf16_f32 v51, v51, v54
	v_mul_f32_e32 v54, 0xbfb8aa3b, v59
	v_cvt_pk_bf16_f32 v52, v52, v53
	v_mul_f32_e32 v53, 0xbfb8aa3b, v58
	v_exp_f32_e32 v53, v53
	v_exp_f32_e32 v54, v54
	v_pk_add_f32 v[24:25], v[24:25], v[72:73]
	v_pk_add_f32 v[14:15], v[14:15], v[70:71]
	v_add_f32_e32 v53, 1.0, v53
	v_add_f32_e32 v54, 1.0, v54
	v_rcp_f32_e32 v53, v53
	v_rcp_f32_e32 v54, v54
	v_pk_add_f32 v[16:17], v[16:17], v[72:73]
	v_pk_add_f32 v[6:7], v[6:7], v[70:71]
	v_pk_add_f32 v[8:9], v[8:9], v[72:73]
	v_cvt_pk_bf16_f32 v53, v53, v54
	global_store_dwordx4 v[126:127], v[50:53], off offset:256
	s_nop 1
	v_pk_add_f32 v[50:51], v[44:45], v[68:69]
	v_pk_add_f32 v[44:45], v[42:43], v[66:67]
	v_mul_f32_e32 v42, 0xbfb8aa3b, v46
	v_mul_f32_e32 v43, 0xbfb8aa3b, v47
	v_exp_f32_e32 v42, v42
	v_exp_f32_e32 v43, v43
	v_mul_f32_e32 v46, 0xbfb8aa3b, v49
	v_mul_f32_e32 v44, 0xbfb8aa3b, v44
	v_add_f32_e32 v42, 1.0, v42
	v_add_f32_e32 v43, 1.0, v43
	v_rcp_f32_e32 v42, v42
	v_rcp_f32_e32 v43, v43
	v_mul_f32_e32 v45, 0xbfb8aa3b, v45
	v_exp_f32_e32 v46, v46
	v_exp_f32_e32 v44, v44
	v_cvt_pk_bf16_f32 v42, v42, v43
	v_mul_f32_e32 v43, 0xbfb8aa3b, v48
	v_exp_f32_e32 v43, v43
	v_exp_f32_e32 v45, v45
	v_add_f32_e32 v46, 1.0, v46
	v_add_f32_e32 v44, 1.0, v44
	v_add_f32_e32 v43, 1.0, v43
	v_add_f32_e32 v45, 1.0, v45
	v_rcp_f32_e32 v43, v43
	v_rcp_f32_e32 v46, v46
	v_rcp_f32_e32 v44, v44
	v_rcp_f32_e32 v45, v45
	v_cvt_pk_bf16_f32 v43, v43, v46
	v_mul_f32_e32 v46, 0xbfb8aa3b, v51
	v_cvt_pk_bf16_f32 v44, v44, v45
	v_mul_f32_e32 v45, 0xbfb8aa3b, v50
	v_exp_f32_e32 v45, v45
	v_exp_f32_e32 v46, v46
	v_add_f32_e32 v45, 1.0, v45
	v_add_f32_e32 v46, 1.0, v46
	v_rcp_f32_e32 v45, v45
	v_rcp_f32_e32 v46, v46
	s_nop 0
	v_cvt_pk_bf16_f32 v45, v45, v46
	global_store_dwordx4 v[114:115], v[42:45], off offset:256
	s_nop 1
	v_pk_add_f32 v[42:43], v[36:37], v[68:69]
	v_pk_add_f32 v[36:37], v[34:35], v[66:67]
	v_mul_f32_e32 v34, 0xbfb8aa3b, v38
	v_mul_f32_e32 v35, 0xbfb8aa3b, v39
	v_exp_f32_e32 v34, v34
	v_exp_f32_e32 v35, v35
	v_mul_f32_e32 v38, 0xbfb8aa3b, v41
	v_mul_f32_e32 v36, 0xbfb8aa3b, v36
	v_add_f32_e32 v34, 1.0, v34
	v_add_f32_e32 v35, 1.0, v35
	v_rcp_f32_e32 v34, v34
	v_rcp_f32_e32 v35, v35
	v_mul_f32_e32 v37, 0xbfb8aa3b, v37
	v_exp_f32_e32 v38, v38
	v_exp_f32_e32 v36, v36
	v_cvt_pk_bf16_f32 v34, v34, v35
	v_mul_f32_e32 v35, 0xbfb8aa3b, v40
	v_exp_f32_e32 v35, v35
	v_exp_f32_e32 v37, v37
	v_add_f32_e32 v38, 1.0, v38
	v_add_f32_e32 v36, 1.0, v36
	v_add_f32_e32 v35, 1.0, v35
	v_add_f32_e32 v37, 1.0, v37
	v_rcp_f32_e32 v35, v35
	v_rcp_f32_e32 v38, v38
	v_rcp_f32_e32 v36, v36
	v_rcp_f32_e32 v37, v37
	v_cvt_pk_bf16_f32 v35, v35, v38
	v_mul_f32_e32 v38, 0xbfb8aa3b, v43
; #define PG8_BAR __builtin_amdgcn_s_barrier()
; __device__ __forceinline__ unsigned cvt_pk(float lo, float hi) { f32x2_t v = {lo, hi}; bf16x2_t b = __builtin_convertvector(v, bf16x2_t); return __builtin_bit_cast(unsigned, b); }
; __device__ __forceinline__ float sigmoidf_(float x) { return __builtin_amdgcn_rcpf(1.0f + ex2(-x * LOG2E)); }
; template <class Epi, class Sched, bool ALIGN_EPI = false, bool SP2 = false>
; __device__ __forceinline__ void gemm_phase(PG8_LAS unsigned char* lds, const Gemm g, const Sched& S, const Epi& E) {
;     ...
;         if constexpr (ALIGN_EPI) { if (wr == 0) PG8_BAR; }
;         bool keep_acc = false;
;         if constexpr (!Epi::AFTER_DRAIN) { if constexpr (Epi::CARRY) keep_acc = E.carry(acc, cur, wr, wc, fr, fq); else E(acc, cur, wr, wc, fr, fq); S.done(cur); }
;         if (!has_next) break;
;         if (!keep_acc)
; #pragma unroll
;         for (int a = 0; a < 2; ++a)
; #pragma unroll
;             for (int b = 0; b < 2; ++b)
; #pragma unroll
;                 for (int m = 0; m < 4; ++m)
; #pragma unroll
;                     for (int n = 0; n < 2; ++n) acc[a][b][m][n] = (f32x4){0.f, 0.f, 0.f, 0.f};
;         cur = nxt; cA = nA; cB = nB; ++ui;
;         if constexpr (ALIGN_EPI) { if (wr == 1) PG8_BAR; }
;     __device__ __forceinline__ void operator()(const f32x4 (&acc)[2][2][4][2], const Unit& u, int wr, int wc, int fr, int fq) const {
;         const int row0 = u.pm * 256 + wr * 64 + fr, col0 = u.pn * 256 + wc * 32 + 8 * fq;
; #pragma unroll
;         for (int bj = 0; bj < 2; ++bj) {
;             const int c = col0 + bj * 128;
;             const f32x4 b0 = *(const f32x4*)(bias + c), b1 = *(const f32x4*)(bias + c + 4);
; #pragma unroll
;             for (int ai = 0; ai < 2; ++ai)
; #pragma unroll
;                 for (int m = 0; m < 4; ++m) {
;                     const f32x4 v0 = acc[ai][bj][m][0] + b0, v1 = acc[ai][bj][m][1] + b1;
;                     u32x4 w; w.x = cvt_pk(sigmoidf_(v0[0]), sigmoidf_(v0[1])); w.y = cvt_pk(sigmoidf_(v0[2]), sigmoidf_(v0[3]));
;                     w.z = cvt_pk(sigmoidf_(v1[0]), sigmoidf_(v1[1])); w.w = cvt_pk(sigmoidf_(v1[2]), sigmoidf_(v1[3]));
;                     *(u32x4*)(G + (size_t)(row0 + ai * 128 + m * 16) * (3 * DM) + c) = w;
;                 }
;         }
;     }
	v_cvt_pk_bf16_f32 v36, v36, v37
	v_mul_f32_e32 v37, 0xbfb8aa3b, v42
	v_exp_f32_e32 v37, v37
	v_exp_f32_e32 v38, v38
	v_add_f32_e32 v37, 1.0, v37
	v_add_f32_e32 v38, 1.0, v38
	v_rcp_f32_e32 v37, v37
	v_rcp_f32_e32 v38, v38
	s_nop 0
	v_cvt_pk_bf16_f32 v37, v37, v38
	global_store_dwordx4 v[98:99], v[34:37], off offset:256
	s_nop 1
	v_pk_add_f32 v[34:35], v[28:29], v[68:69]
	v_pk_add_f32 v[28:29], v[26:27], v[66:67]
	v_mul_f32_e32 v26, 0xbfb8aa3b, v30
	v_mul_f32_e32 v27, 0xbfb8aa3b, v31
	v_exp_f32_e32 v26, v26
	v_exp_f32_e32 v27, v27
	v_mul_f32_e32 v30, 0xbfb8aa3b, v33
	v_mul_f32_e32 v28, 0xbfb8aa3b, v28
	v_add_f32_e32 v26, 1.0, v26
	v_add_f32_e32 v27, 1.0, v27
	v_rcp_f32_e32 v26, v26
	v_rcp_f32_e32 v27, v27
	v_mul_f32_e32 v29, 0xbfb8aa3b, v29
	v_exp_f32_e32 v30, v30
	v_exp_f32_e32 v28, v28
	v_cvt_pk_bf16_f32 v26, v26, v27
	v_mul_f32_e32 v27, 0xbfb8aa3b, v32
	v_exp_f32_e32 v27, v27
	v_exp_f32_e32 v29, v29
	v_add_f32_e32 v30, 1.0, v30
	v_add_f32_e32 v28, 1.0, v28
	v_add_f32_e32 v27, 1.0, v27
	v_add_f32_e32 v29, 1.0, v29
	v_rcp_f32_e32 v27, v27
	v_rcp_f32_e32 v30, v30
	v_rcp_f32_e32 v28, v28
	v_rcp_f32_e32 v29, v29
	v_cvt_pk_bf16_f32 v27, v27, v30
	v_mul_f32_e32 v30, 0xbfb8aa3b, v35
	v_cvt_pk_bf16_f32 v28, v28, v29
	v_mul_f32_e32 v29, 0xbfb8aa3b, v34
	v_exp_f32_e32 v29, v29
	v_exp_f32_e32 v30, v30
	v_add_f32_e32 v29, 1.0, v29
	v_add_f32_e32 v30, 1.0, v30
	v_rcp_f32_e32 v29, v29
	v_rcp_f32_e32 v30, v30
	s_nop 0
	v_cvt_pk_bf16_f32 v29, v29, v30
	global_store_dwordx4 v[90:91], v[26:29], off offset:256
	s_nop 1
	v_pk_add_f32 v[26:27], v[20:21], v[68:69]
	v_pk_add_f32 v[20:21], v[18:19], v[66:67]
	v_mul_f32_e32 v18, 0xbfb8aa3b, v22
	v_mul_f32_e32 v19, 0xbfb8aa3b, v23
	v_exp_f32_e32 v18, v18
	v_exp_f32_e32 v19, v19
	v_mul_f32_e32 v22, 0xbfb8aa3b, v25
	v_mul_f32_e32 v20, 0xbfb8aa3b, v20
	v_add_f32_e32 v18, 1.0, v18
	v_add_f32_e32 v19, 1.0, v19
	v_rcp_f32_e32 v18, v18
	v_rcp_f32_e32 v19, v19
	v_mul_f32_e32 v21, 0xbfb8aa3b, v21
	v_exp_f32_e32 v22, v22
	v_exp_f32_e32 v20, v20
	v_cvt_pk_bf16_f32 v18, v18, v19
	v_mul_f32_e32 v19, 0xbfb8aa3b, v24
	v_exp_f32_e32 v19, v19
	v_exp_f32_e32 v21, v21
	v_add_f32_e32 v22, 1.0, v22
	v_add_f32_e32 v20, 1.0, v20
	v_add_f32_e32 v19, 1.0, v19
	v_add_f32_e32 v21, 1.0, v21
	v_rcp_f32_e32 v19, v19
	v_rcp_f32_e32 v22, v22
	v_rcp_f32_e32 v20, v20
	v_rcp_f32_e32 v21, v21
	v_cvt_pk_bf16_f32 v19, v19, v22
	v_mul_f32_e32 v22, 0xbfb8aa3b, v27
	v_cvt_pk_bf16_f32 v20, v20, v21
	v_mul_f32_e32 v21, 0xbfb8aa3b, v26
	v_exp_f32_e32 v21, v21
	v_exp_f32_e32 v22, v22
	v_add_f32_e32 v21, 1.0, v21
	v_add_f32_e32 v22, 1.0, v22
	v_rcp_f32_e32 v21, v21
	v_rcp_f32_e32 v22, v22
	s_nop 0
	v_cvt_pk_bf16_f32 v21, v21, v22
	global_store_dwordx4 v[82:83], v[18:21], off offset:256
	s_nop 1
	v_pk_add_f32 v[18:19], v[12:13], v[68:69]
	v_pk_add_f32 v[12:13], v[10:11], v[66:67]
	v_mul_f32_e32 v10, 0xbfb8aa3b, v14
	v_mul_f32_e32 v11, 0xbfb8aa3b, v15
	v_exp_f32_e32 v10, v10
	v_exp_f32_e32 v11, v11
	v_mul_f32_e32 v14, 0xbfb8aa3b, v17
	v_mul_f32_e32 v12, 0xbfb8aa3b, v12
	v_add_f32_e32 v10, 1.0, v10
	v_add_f32_e32 v11, 1.0, v11
	v_rcp_f32_e32 v10, v10
	v_rcp_f32_e32 v11, v11
	v_mul_f32_e32 v13, 0xbfb8aa3b, v13
	v_exp_f32_e32 v14, v14
	v_exp_f32_e32 v12, v12
	v_cvt_pk_bf16_f32 v10, v10, v11
	v_mul_f32_e32 v11, 0xbfb8aa3b, v16
	v_exp_f32_e32 v11, v11
	v_exp_f32_e32 v13, v13
	v_add_f32_e32 v14, 1.0, v14
	v_add_f32_e32 v12, 1.0, v12
	v_add_f32_e32 v11, 1.0, v11
	v_add_f32_e32 v13, 1.0, v13
	v_rcp_f32_e32 v11, v11
	v_rcp_f32_e32 v14, v14
	v_rcp_f32_e32 v12, v12
	v_rcp_f32_e32 v13, v13
	v_cvt_pk_bf16_f32 v11, v11, v14
	v_mul_f32_e32 v14, 0xbfb8aa3b, v19
	v_cvt_pk_bf16_f32 v12, v12, v13
	v_mul_f32_e32 v13, 0xbfb8aa3b, v18
	v_exp_f32_e32 v13, v13
	v_exp_f32_e32 v14, v14
	v_add_f32_e32 v13, 1.0, v13
	v_add_f32_e32 v14, 1.0, v14
	v_rcp_f32_e32 v13, v13
	v_rcp_f32_e32 v14, v14
	s_nop 0
	v_cvt_pk_bf16_f32 v13, v13, v14
	global_store_dwordx4 v[74:75], v[10:13], off offset:256
	s_nop 1
	v_pk_add_f32 v[10:11], v[4:5], v[68:69]
	v_pk_add_f32 v[4:5], v[2:3], v[66:67]
	v_mul_f32_e32 v2, 0xbfb8aa3b, v6
	v_mul_f32_e32 v3, 0xbfb8aa3b, v7
	v_exp_f32_e32 v2, v2
	v_exp_f32_e32 v3, v3
	v_mul_f32_e32 v6, 0xbfb8aa3b, v9
	v_mul_f32_e32 v4, 0xbfb8aa3b, v4
	v_add_f32_e32 v2, 1.0, v2
	v_add_f32_e32 v3, 1.0, v3
	v_rcp_f32_e32 v2, v2
	v_rcp_f32_e32 v3, v3
	v_mul_f32_e32 v5, 0xbfb8aa3b, v5
	v_exp_f32_e32 v6, v6
	v_exp_f32_e32 v4, v4
	v_cvt_pk_bf16_f32 v2, v2, v3
	v_mul_f32_e32 v3, 0xbfb8aa3b, v8
	v_exp_f32_e32 v3, v3
	v_exp_f32_e32 v5, v5
	v_add_f32_e32 v6, 1.0, v6
	v_add_f32_e32 v4, 1.0, v4
	v_add_f32_e32 v3, 1.0, v3
	v_add_f32_e32 v5, 1.0, v5
	v_rcp_f32_e32 v3, v3
	v_rcp_f32_e32 v6, v6
	v_rcp_f32_e32 v4, v4
	v_rcp_f32_e32 v5, v5
	v_cvt_pk_bf16_f32 v3, v3, v6
	v_mul_f32_e32 v6, 0xbfb8aa3b, v11
	v_cvt_pk_bf16_f32 v4, v4, v5
	v_mul_f32_e32 v5, 0xbfb8aa3b, v10
	v_exp_f32_e32 v5, v5
	v_exp_f32_e32 v6, v6
	v_add_f32_e32 v5, 1.0, v5
	v_add_f32_e32 v6, 1.0, v6
	v_rcp_f32_e32 v5, v5
	v_rcp_f32_e32 v6, v6
	s_nop 0
	v_cvt_pk_bf16_f32 v5, v5, v6
	global_store_dwordx4 v[76:77], v[2:5], off offset:256
	s_cbranch_vccnz .LBB0_125
	s_andn2_b64 vcc, exec, s[0:1]
	s_cbranch_vccnz .LBB0_124
	s_barrier
	s_branch .LBB0_124
	s_nop 0
